# memory K/V projection GEMM moved from the FFN1-down phase (where it left half the workgroups idle) into the dynamically balanced token-mixer phase
# speedup vs baseline: 1.0068x; 1.0068x over previous
.Lmemkv_skip:
	s_mov_b64 s[8:9], s[98:99]
	v_mov_b32_e32 v0, v206
	v_mov_b32_e32 v64, v206
	s_nop 1
	s_load_dwordx4 s[40:43], s[0:1], 0x78
	s_load_dwordx2 s[52:53], s[0:1], 0x98
	s_add_u32 s50, s38, 0x11f00000
	s_addc_u32 s51, s39, 0
	s_and_b32 s76, s2, 3
	v_readfirstlane_b32 s10, v64
	s_lshl_b32 s75, s76, 7
	s_ashr_i32 s35, s10, 6
	s_cmpk_gt_i32 s2, 0x7f
	v_and_b32_e32 v66, 63, v64
	s_cbranch_scc0 .LBB0_517
	s_add_i32 s77, s2, 0xffffff80
	s_lshl_b32 s10, s77, 3
	s_add_i32 s26, s34, 0xfffffc00
	s_add_i32 s10, s35, s10
	v_lshlrev_b32_e32 v172, 4, v66
	v_lshlrev_b32_e32 v173, 5, v66
	s_and_b32 s11, s10, 0x1ff
	s_lshr_b32 s12, s10, 9
	s_lshl_b32 s12, s12, 11
	s_add_u32 s12, s12, s11
	s_add_u32 s12, s12, 0x600
	s_mul_i32 s13, s12, 0x2c00
	s_mul_hi_u32 s20, s12, 0x2c00
	s_add_u32 s96, s50, s13
	s_addc_u32 s97, s51, s20
	global_load_dwordx4 v[0:3], v172, s[96:97] offset:1024
	global_load_dwordx4 v[4:7], v172, s[96:97] offset:2048
	s_add_u32 s96, s96, 0x2c00000
	s_addc_u32 s97, s97, 0
	global_load_dwordx4 v[8:11], v172, s[96:97] offset:1024
	global_load_dwordx4 v[12:15], v172, s[96:97] offset:2048
	s_add_u32 s96, s96, 0x2c00000
	s_addc_u32 s97, s97, 0
	global_load_dwordx4 v[16:19], v172, s[96:97] offset:1024
	global_load_dwordx4 v[20:23], v172, s[96:97] offset:2048
	s_add_u32 s96, s96, 0x2c00000
	s_addc_u32 s97, s97, 0
	global_load_dwordx4 v[24:27], v172, s[96:97] offset:1024
	global_load_dwordx4 v[28:31], v172, s[96:97] offset:2048
	s_add_u32 s96, s96, 0x2c00000
	s_addc_u32 s97, s97, 0
	global_load_dwordx4 v[32:35], v172, s[96:97] offset:1024
	global_load_dwordx4 v[36:39], v172, s[96:97] offset:2048
	s_add_u32 s96, s96, 0x2c00000
	s_addc_u32 s97, s97, 0
	global_load_dwordx4 v[40:43], v172, s[96:97] offset:1024
	global_load_dwordx4 v[44:47], v172, s[96:97] offset:2048
	s_add_u32 s96, s96, 0x2c00000
	s_addc_u32 s97, s97, 0
	global_load_dwordx4 v[48:51], v172, s[96:97] offset:1024
	global_load_dwordx4 v[52:55], v172, s[96:97] offset:2048
	s_add_u32 s96, s96, 0x2c00000
	s_addc_u32 s97, s97, 0
	global_load_dwordx4 v[56:59], v172, s[96:97] offset:1024
	global_load_dwordx4 v[60:63], v172, s[96:97] offset:2048
	s_add_u32 s96, s96, 0x2c00000
	s_addc_u32 s97, s97, 0
	global_load_dwordx4 v[68:71], v172, s[96:97] offset:1024
	global_load_dwordx4 v[72:75], v172, s[96:97] offset:2048
	s_add_u32 s96, s96, 0x2c00000
	s_addc_u32 s97, s97, 0
	global_load_dwordx4 v[76:79], v172, s[96:97] offset:1024
	global_load_dwordx4 v[80:83], v172, s[96:97] offset:2048
	s_add_u32 s96, s96, 0x2c00000
	s_addc_u32 s97, s97, 0
	global_load_dwordx4 v[84:87], v172, s[96:97] offset:1024
	global_load_dwordx4 v[88:91], v172, s[96:97] offset:2048
	s_add_u32 s96, s96, 0x2c00000
	s_addc_u32 s97, s97, 0
	global_load_dwordx4 v[92:95], v172, s[96:97] offset:1024
	global_load_dwordx4 v[96:99], v172, s[96:97] offset:2048
	s_add_u32 s96, s96, 0x2c00000
	s_addc_u32 s97, s97, 0
	global_load_dwordx4 v[100:103], v172, s[96:97] offset:1024
	global_load_dwordx4 v[104:107], v172, s[96:97] offset:2048
	s_add_u32 s96, s96, 0x2c00000
	s_addc_u32 s97, s97, 0
	global_load_dwordx4 v[108:111], v172, s[96:97] offset:1024
	global_load_dwordx4 v[112:115], v172, s[96:97] offset:2048
	s_add_u32 s96, s96, 0x2c00000
	s_addc_u32 s97, s97, 0
	global_load_dwordx4 v[116:119], v172, s[96:97] offset:1024
	global_load_dwordx4 v[120:123], v172, s[96:97] offset:2048
	s_add_u32 s96, s96, 0x2c00000
	s_addc_u32 s97, s97, 0
	global_load_dwordx4 v[124:127], v172, s[96:97] offset:1024
	global_load_dwordx4 v[128:131], v172, s[96:97] offset:2048
	s_cmp_lt_u32 s10, 0x100
	s_cbranch_scc0 .Lcc_no17
	s_add_u32 s12, s10, 0x10000
	s_mul_i32 s13, s12, 0x2c00
	s_mul_hi_u32 s20, s12, 0x2c00
	s_add_u32 s96, s50, s13
	s_addc_u32 s97, s51, s20
	global_load_dwordx4 v[132:135], v172, s[96:97] offset:1024
	global_load_dwordx4 v[136:139], v172, s[96:97] offset:2048
